# ag_rows pooling-row loads de-serialized (15 exec-masked loads each followed by vmcnt(0) -> loads into pre-zeroed temporaries, one wait per group); conv split 3552
# baseline (speedup 1.0000x reference)
.LBB0_370:
	s_movk_i32 s10, 0x400
	v_cmp_gt_i32_e32 vcc, s10, v128
	v_mov_b32_e32 v104, 0
	v_mov_b32_e32 v105, 0
	v_cndmask_b32_e64 v13, v132, 0, vcc
	v_cndmask_b32_e32 v136, v133, v134, vcc
	v_add_u32_e32 v38, v130, v13
	v_cmp_lt_u32_e32 vcc, v38, v136
	v_mov_b32_e32 v106, 0
	v_mov_b32_e32 v107, 0
	v_mov_b32_e32 v190, 0
	v_mov_b32_e32 v191, 0
	s_and_saveexec_b64 s[10:11], vcc
	s_cbranch_execz .LBB0_372
	v_mad_u64_u32 v[14:15], s[12:13], v130, s92, v[8:9]
	v_add_co_u32_e32 v14, vcc, 0x1000, v14
	s_nop 1
	v_addc_co_u32_e32 v15, vcc, 0, v15, vcc
	global_load_dwordx2 v[190:191], v[14:15], off offset:1280
.LBB0_372:
	s_or_b64 exec, exec, s[10:11]
	v_add_u32_e32 v14, 1, v38
	v_cmp_lt_u32_e32 vcc, v14, v136
	v_mov_b32_e32 v82, 0
	v_mov_b32_e32 v66, 0
	v_mov_b32_e32 v67, 0
	v_mov_b32_e32 v68, 0
	v_mov_b32_e32 v69, 0
	v_mov_b32_e32 v192, 0
	v_mov_b32_e32 v193, 0
	s_and_saveexec_b64 s[10:11], vcc
	s_cbranch_execz .LBB0_374
	v_add_u32_e32 v14, 1, v130
	v_mad_u64_u32 v[14:15], s[12:13], v14, s92, v[8:9]
	v_add_co_u32_e32 v14, vcc, 0x1000, v14
	s_nop 1
	v_addc_co_u32_e32 v15, vcc, 0, v15, vcc
	global_load_dwordx2 v[192:193], v[14:15], off offset:1280
.LBB0_374:
	s_or_b64 exec, exec, s[10:11]
	v_add_u32_e32 v14, 2, v38
	v_cmp_lt_u32_e32 vcc, v14, v136
	v_mov_b32_e32 v83, 0
	v_mov_b32_e32 v86, 0
	v_mov_b32_e32 v87, 0
	v_mov_b32_e32 v194, 0
	v_mov_b32_e32 v195, 0
	s_and_saveexec_b64 s[10:11], vcc
	s_cbranch_execz .LBB0_376
	v_add_u32_e32 v14, 2, v130
	v_mad_u64_u32 v[14:15], s[12:13], v14, s92, v[8:9]
	v_add_co_u32_e32 v14, vcc, 0x1000, v14
	s_nop 1
	v_addc_co_u32_e32 v15, vcc, 0, v15, vcc
	global_load_dwordx2 v[194:195], v[14:15], off offset:1280
.LBB0_376:
	s_or_b64 exec, exec, s[10:11]
	v_add_u32_e32 v14, 3, v38
	v_cmp_lt_u32_e32 vcc, v14, v136
	v_mov_b32_e32 v64, 0
	v_mov_b32_e32 v80, 0
	v_mov_b32_e32 v81, 0
	v_mov_b32_e32 v84, 0
	v_mov_b32_e32 v85, 0
	v_mov_b32_e32 v196, 0
	v_mov_b32_e32 v197, 0
	s_and_saveexec_b64 s[10:11], vcc
	s_cbranch_execz .LBB0_378
	v_add_u32_e32 v14, 3, v130
	v_mad_u64_u32 v[14:15], s[12:13], v14, s92, v[8:9]
	v_add_co_u32_e32 v14, vcc, 0x1000, v14
	s_nop 1
	v_addc_co_u32_e32 v15, vcc, 0, v15, vcc
	global_load_dwordx2 v[196:197], v[14:15], off offset:1280
.LBB0_378:
	s_or_b64 exec, exec, s[10:11]
	v_add_u32_e32 v14, 4, v38
	v_cmp_lt_u32_e32 vcc, v14, v136
	v_mov_b32_e32 v65, 0
	v_mov_b32_e32 v74, 0
	v_mov_b32_e32 v75, 0
	v_mov_b32_e32 v198, 0
	v_mov_b32_e32 v199, 0
	s_and_saveexec_b64 s[10:11], vcc
	s_cbranch_execz .LBB0_380
	v_add_u32_e32 v14, 4, v130
	v_mad_u64_u32 v[14:15], s[12:13], v14, s92, v[8:9]
	v_add_co_u32_e32 v14, vcc, 0x1000, v14
	s_nop 1
	v_addc_co_u32_e32 v15, vcc, 0, v15, vcc
	global_load_dwordx2 v[198:199], v[14:15], off offset:1280
.LBB0_380:
	s_or_b64 exec, exec, s[10:11]
	v_add_u32_e32 v14, 5, v38
	v_cmp_lt_u32_e32 vcc, v14, v136
	v_mov_b32_e32 v50, 0
	v_mov_b32_e32 v60, 0
	v_mov_b32_e32 v61, 0
	v_mov_b32_e32 v62, 0
	v_mov_b32_e32 v63, 0
	v_mov_b32_e32 v200, 0
	v_mov_b32_e32 v201, 0
	s_and_saveexec_b64 s[10:11], vcc
	s_cbranch_execz .LBB0_382
	v_add_u32_e32 v14, 5, v130
	v_mad_u64_u32 v[14:15], s[12:13], v14, s92, v[8:9]
	v_add_co_u32_e32 v14, vcc, 0x1000, v14
	s_nop 1
	v_addc_co_u32_e32 v15, vcc, 0, v15, vcc
	global_load_dwordx2 v[200:201], v[14:15], off offset:1280
.LBB0_382:
	s_or_b64 exec, exec, s[10:11]
	v_add_u32_e32 v14, 6, v38
	v_cmp_lt_u32_e32 vcc, v14, v136
	v_mov_b32_e32 v51, 0
	v_mov_b32_e32 v54, 0
	v_mov_b32_e32 v55, 0
	v_mov_b32_e32 v202, 0
	v_mov_b32_e32 v203, 0
	s_and_saveexec_b64 s[10:11], vcc
	s_cbranch_execz .LBB0_384
	v_add_u32_e32 v14, 6, v130
	v_mad_u64_u32 v[14:15], s[12:13], v14, s92, v[8:9]
	v_add_co_u32_e32 v14, vcc, 0x1000, v14
	s_nop 1
	v_addc_co_u32_e32 v15, vcc, 0, v15, vcc
	global_load_dwordx2 v[202:203], v[14:15], off offset:1280
.LBB0_384:
	s_or_b64 exec, exec, s[10:11]
	v_add_u32_e32 v14, 7, v38
	v_cmp_lt_u32_e64 s[10:11], v14, v136
	v_mov_b32_e32 v120, 0
	v_add_u32_e32 v46, 7, v130
	v_mov_b32_e32 v42, 0
	v_mov_b32_e32 v43, 0
	v_mov_b32_e32 v44, 0
	v_mov_b32_e32 v45, 0
	v_mov_b32_e32 v204, 0
	v_mov_b32_e32 v205, 0
	s_and_saveexec_b64 s[12:13], s[10:11]
	s_cbranch_execz .LBB0_386
	v_mad_u64_u32 v[14:15], s[14:15], v46, s92, v[8:9]
	v_add_co_u32_e32 v14, vcc, 0x1000, v14
	s_nop 1
	v_addc_co_u32_e32 v15, vcc, 0, v15, vcc
	global_load_dwordx2 v[204:205], v[14:15], off offset:1280
.LBB0_386:
	s_or_b64 exec, exec, s[12:13]
	s_waitcnt vmcnt(0)
	v_and_b32_e32 v105, 0xffff0000, v190
	v_and_b32_e32 v107, 0xffff0000, v191
	v_lshlrev_b32_e32 v104, 16, v190
	v_lshlrev_b32_e32 v106, 16, v191
	v_and_b32_e32 v67, 0xffff0000, v192
	v_and_b32_e32 v69, 0xffff0000, v193
	v_lshlrev_b32_e32 v66, 16, v192
	v_lshlrev_b32_e32 v68, 16, v193
	v_and_b32_e32 v83, 0xffff0000, v194
	v_and_b32_e32 v87, 0xffff0000, v195
	v_lshlrev_b32_e32 v82, 16, v194
	v_lshlrev_b32_e32 v86, 16, v195
	v_and_b32_e32 v81, 0xffff0000, v196
	v_and_b32_e32 v85, 0xffff0000, v197
	v_lshlrev_b32_e32 v80, 16, v196
	v_lshlrev_b32_e32 v84, 16, v197
	v_and_b32_e32 v65, 0xffff0000, v198
	v_and_b32_e32 v75, 0xffff0000, v199
	v_lshlrev_b32_e32 v64, 16, v198
	v_lshlrev_b32_e32 v74, 16, v199
	v_and_b32_e32 v61, 0xffff0000, v200
	v_and_b32_e32 v63, 0xffff0000, v201
	v_lshlrev_b32_e32 v60, 16, v200
	v_lshlrev_b32_e32 v62, 16, v201
	v_and_b32_e32 v51, 0xffff0000, v202
	v_and_b32_e32 v55, 0xffff0000, v203
	v_lshlrev_b32_e32 v50, 16, v202
	v_lshlrev_b32_e32 v54, 16, v203
	v_and_b32_e32 v43, 0xffff0000, v204
	v_and_b32_e32 v45, 0xffff0000, v205
	v_lshlrev_b32_e32 v42, 16, v204
	v_lshlrev_b32_e32 v44, 16, v205
	v_add_u32_e32 v14, 8, v38
	v_add_u32_e32 v70, 8, v130
	v_cmp_lt_u32_e64 s[12:13], v14, v136
	v_mov_b32_e32 v121, 0
	s_and_saveexec_b64 s[14:15], s[12:13]
	s_cbranch_execz .LBB0_388
	v_mad_u64_u32 v[14:15], s[16:17], v70, s92, v[8:9]
	v_add_co_u32_e32 v14, vcc, 0x1000, v14
	s_nop 1
	v_addc_co_u32_e32 v15, vcc, 0, v15, vcc
	global_load_dwordx2 v[120:121], v[14:15], off offset:1280

.LBB0_418:
	s_or_b64 exec, exec, s[46:47]
	v_add_u32_e32 v15, 24, v38
	v_cmp_lt_u32_e64 s[46:47], v15, v136
	v_add_u32_e32 v47, 24, v130
	v_mov_b32_e32 v16, 0
	v_mov_b32_e32 v17, 0
	v_mov_b32_e32 v18, 0
	v_mov_b32_e32 v19, 0
	v_mov_b32_e32 v206, 0
	v_mov_b32_e32 v207, 0
	s_and_saveexec_b64 s[96:97], s[46:47]
	s_cbranch_execz .LBB0_420
	v_mad_u64_u32 v[16:17], vcc, v47, s92, v[8:9]
	v_add_co_u32_e32 v16, vcc, 0x1000, v16
	s_nop 1
	v_addc_co_u32_e32 v17, vcc, 0, v17, vcc
	global_load_dwordx2 v[206:207], v[16:17], off offset:1280
.LBB0_420:
	s_or_b64 exec, exec, s[96:97]
	v_add_u32_e32 v15, 25, v38
	v_cmp_lt_u32_e32 vcc, v15, v136
	v_mov_b32_e32 v15, 0
	v_mov_b32_e32 v20, 0
	v_mov_b32_e32 v21, 0
	v_mov_b32_e32 v208, 0
	v_mov_b32_e32 v209, 0
	s_and_saveexec_b64 s[96:97], vcc
	s_cbranch_execz .LBB0_422
	v_add_u32_e32 v14, 25, v130
	v_mad_u64_u32 v[14:15], vcc, v14, s92, v[8:9]
	v_add_co_u32_e32 v14, vcc, 0x1000, v14
	s_nop 1
	v_addc_co_u32_e32 v15, vcc, 0, v15, vcc
	global_load_dwordx2 v[208:209], v[14:15], off offset:1280
.LBB0_422:
	s_or_b64 exec, exec, s[96:97]
	v_add_u32_e32 v22, 26, v38
	v_cmp_lt_u32_e32 vcc, v22, v136
	v_mov_b32_e32 v22, 0
	v_mov_b32_e32 v24, 0
	v_mov_b32_e32 v25, 0
	v_mov_b32_e32 v26, 0
	v_mov_b32_e32 v27, 0
	v_mov_b32_e32 v210, 0
	v_mov_b32_e32 v211, 0
	s_and_saveexec_b64 s[96:97], vcc
	s_cbranch_execz .LBB0_424
	v_add_u32_e32 v23, 26, v130
	v_mad_u64_u32 v[24:25], vcc, v23, s92, v[8:9]
	v_add_co_u32_e32 v24, vcc, 0x1000, v24
	s_nop 1
	v_addc_co_u32_e32 v25, vcc, 0, v25, vcc
	global_load_dwordx2 v[210:211], v[24:25], off offset:1280
.LBB0_424:
	s_or_b64 exec, exec, s[96:97]
	v_add_u32_e32 v23, 27, v38
	v_cmp_lt_u32_e32 vcc, v23, v136
	v_mov_b32_e32 v23, 0
	v_mov_b32_e32 v28, 0
	v_mov_b32_e32 v29, 0
	v_mov_b32_e32 v212, 0
	v_mov_b32_e32 v213, 0
	s_and_saveexec_b64 s[96:97], vcc
	s_cbranch_execz .LBB0_426
	v_add_u32_e32 v22, 27, v130
	v_mad_u64_u32 v[22:23], vcc, v22, s92, v[8:9]
	v_add_co_u32_e32 v22, vcc, 0x1000, v22
	s_nop 1
	v_addc_co_u32_e32 v23, vcc, 0, v23, vcc
	global_load_dwordx2 v[212:213], v[22:23], off offset:1280
.LBB0_426:
	s_or_b64 exec, exec, s[96:97]
	v_add_u32_e32 v30, 28, v38
	v_cmp_lt_u32_e32 vcc, v30, v136
	v_mov_b32_e32 v30, 0
	v_mov_b32_e32 v32, 0
	v_mov_b32_e32 v33, 0
	v_mov_b32_e32 v34, 0
	v_mov_b32_e32 v35, 0
	v_mov_b32_e32 v214, 0
	v_mov_b32_e32 v215, 0
	s_and_saveexec_b64 s[96:97], vcc
	s_cbranch_execz .LBB0_428
	v_add_u32_e32 v31, 28, v130
	v_mad_u64_u32 v[32:33], vcc, v31, s92, v[8:9]
	v_add_co_u32_e32 v32, vcc, 0x1000, v32
	s_nop 1
	v_addc_co_u32_e32 v33, vcc, 0, v33, vcc
	global_load_dwordx2 v[214:215], v[32:33], off offset:1280
.LBB0_428:
	s_or_b64 exec, exec, s[96:97]
	v_add_u32_e32 v31, 29, v38
	v_cmp_lt_u32_e32 vcc, v31, v136
	v_mov_b32_e32 v31, 0
	v_mov_b32_e32 v36, 0
	v_mov_b32_e32 v37, 0
	v_mov_b32_e32 v216, 0
	v_mov_b32_e32 v217, 0
	s_and_saveexec_b64 s[96:97], vcc
	s_cbranch_execz .LBB0_430
	v_add_u32_e32 v30, 29, v130
	v_mad_u64_u32 v[30:31], vcc, v30, s92, v[8:9]
	v_add_co_u32_e32 v30, vcc, 0x1000, v30
	s_nop 1
	v_addc_co_u32_e32 v31, vcc, 0, v31, vcc
	global_load_dwordx2 v[216:217], v[30:31], off offset:1280
.LBB0_430:
	s_or_b64 exec, exec, s[96:97]
	v_add_u32_e32 v38, 30, v38
	v_cmp_lt_u32_e32 vcc, v38, v136
	v_mov_b32_e32 v71, 0
	v_mov_b32_e32 v40, 0
	v_mov_b32_e32 v41, 0
	v_mov_b32_e32 v38, 0
	v_mov_b32_e32 v39, 0
	v_mov_b32_e32 v218, 0
	v_mov_b32_e32 v219, 0
	s_and_saveexec_b64 s[96:97], vcc
	s_cbranch_execz .LBB0_432
	v_add_u32_e32 v38, 30, v130
	v_mad_u64_u32 v[38:39], vcc, v38, s92, v[8:9]
	v_add_co_u32_e32 v38, vcc, 0x1000, v38
	s_nop 1
	v_addc_co_u32_e32 v39, vcc, 0, v39, vcc
	global_load_dwordx2 v[218:219], v[38:39], off offset:1280
.LBB0_432:
	s_or_b64 exec, exec, s[96:97]
	s_waitcnt vmcnt(0)
	v_and_b32_e32 v17, 0xffff0000, v206
	v_and_b32_e32 v19, 0xffff0000, v207
	v_lshlrev_b32_e32 v16, 16, v206
	v_lshlrev_b32_e32 v18, 16, v207
	v_and_b32_e32 v15, 0xffff0000, v208
	v_and_b32_e32 v21, 0xffff0000, v209
	v_lshlrev_b32_e32 v14, 16, v208
	v_lshlrev_b32_e32 v20, 16, v209
	v_and_b32_e32 v25, 0xffff0000, v210
	v_and_b32_e32 v27, 0xffff0000, v211
	v_lshlrev_b32_e32 v24, 16, v210
	v_lshlrev_b32_e32 v26, 16, v211
	v_and_b32_e32 v23, 0xffff0000, v212
	v_and_b32_e32 v29, 0xffff0000, v213
	v_lshlrev_b32_e32 v22, 16, v212
	v_lshlrev_b32_e32 v28, 16, v213
	v_and_b32_e32 v33, 0xffff0000, v214
	v_and_b32_e32 v35, 0xffff0000, v215
	v_lshlrev_b32_e32 v32, 16, v214
	v_lshlrev_b32_e32 v34, 16, v215
	v_and_b32_e32 v31, 0xffff0000, v216
	v_and_b32_e32 v37, 0xffff0000, v217
	v_lshlrev_b32_e32 v30, 16, v216
	v_lshlrev_b32_e32 v36, 16, v217
	v_and_b32_e32 v41, 0xffff0000, v218
	v_and_b32_e32 v39, 0xffff0000, v219
	v_lshlrev_b32_e32 v40, 16, v218
	v_lshlrev_b32_e32 v38, 16, v219
	s_and_saveexec_b64 s[96:97], s[10:11]
	s_cbranch_execz .LBB0_434
	v_mad_u64_u32 v[72:73], s[10:11], v46, s92, v[10:11]
	global_load_dword v71, v[72:73], off

.LBB0_469:
	s_add_i32 s0, s33, 0xffffff10
	s_cmpk_gt_u32 s0, 0xaff
	s_cbranch_scc1 .LBB0_492
	v_lshlrev_b32_e32 v2, 2, v1
	v_lshrrev_b32_e32 v3, 3, v188
	v_add_u32_e32 v39, 0, v2
	v_readlane_b32 s8, v254, 0
	v_and_b32_e32 v26, 0x78, v3
	v_or_b32_e32 v33, 7, v3
	v_lshl_add_u32 v3, v1, 8, v39
	v_readlane_b32 s9, v254, 1
	v_readlane_b32 s10, v254, 2
	v_readlane_b32 s11, v254, 3
	v_readlane_b32 s12, v254, 4
	v_readlane_b32 s13, v254, 5
	v_lshl_add_u32 v34, v26, 2, v3
	v_lshl_add_u32 v35, v33, 2, v3
	v_mov_b32_e32 v3, 0
	v_readlane_b32 s14, v254, 6
	v_readlane_b32 s15, v254, 7
	s_mov_b64 s[6:7], s[10:11]
	s_mov_b64 s[8:9], s[12:13]
	v_lshl_add_u64 v[4:5], s[8:9], 0, v[2:3]
	v_lshl_add_u64 v[6:7], s[72:73], 0, v[2:3]
	v_lshl_add_u64 v[8:9], s[70:71], 0, v[2:3]
	v_lshl_add_u64 v[10:11], s[68:69], 0, v[2:3]
	v_lshl_add_u64 v[12:13], s[6:7], 0, v[2:3]
	v_lshl_add_u64 v[14:15], s[74:75], 0, v[2:3]
	v_lshlrev_b32_e32 v2, 1, v1
	v_lshl_add_u64 v[16:17], s[86:87], 0, v[2:3]
	s_mov_b64 s[2:3], 0x1880000
	v_lshl_add_u64 v[18:19], v[16:17], 0, s[2:3]
	s_mov_b64 s[2:3], 0x1300000
	s_add_i32 s4, s33, 0x1f0
	v_mul_u32_u24_e32 v38, 0x104, v26
	s_mov_b64 s[10:11], s[14:15]
	v_lshl_add_u64 v[20:21], v[16:17], 0, s[2:3]
	s_mov_b64 s[2:3], 0x800000
	v_mul_u32_u24_e32 v40, 0x104, v33
	v_lshl_add_u64 v[22:23], v[16:17], 0, s[2:3]
	s_mov_b64 s[2:3], 0x600000
	s_lshl_b32 s6, s50, 6
	s_mul_i32 s8, s50, 0x2e000
	v_lshrrev_b32_e32 v2, 6, v188
	s_lshl_b32 s0, s4, 2
	s_lshl_b32 s10, s50, 2
	v_add_u32_e32 v38, v39, v38
	s_mov_b32 s1, 0
	v_or_b32_e32 v27, 1, v26
	v_or_b32_e32 v28, 2, v26
	v_or_b32_e32 v29, 3, v26
	v_or_b32_e32 v30, 4, v26
	v_or_b32_e32 v31, 5, v26
	v_or_b32_e32 v32, 6, v26
	v_lshl_add_u64 v[24:25], v[16:17], 0, s[2:3]
	s_lshl_b32 s5, s4, 6
	s_addk_i32 s6, 0xc400
	v_mul_u32_u24_e32 v36, 0xb80, v33
	s_mul_i32 s7, s4, 0x2e000
	s_add_i32 s8, s8, 0xfd4e0000
	v_mul_u32_u24_e32 v37, 0x5c00, v2
	s_add_i32 s9, s0, 0x3cf80
	s_addk_i32 s10, 0xfc40
	v_add_u32_e32 v39, v39, v40
	s_movk_i32 s11, 0x7fff
	s_mov_b32 s12, 0xfff00
	s_mov_b32 s13, 0x40000
	v_add_u32_e32 v40, 0x400, v38
	s_branch .LBB0_472
.LBB0_471:
	s_add_i32 s4, s4, s95
	s_add_i32 s5, s5, s6
	s_add_i32 s7, s7, s8
	s_add_i32 s9, s9, s10
	s_cmpk_lt_i32 s4, 0xde0
	s_cbranch_scc0 .LBB0_492

.LBB0_731:
	s_add_i32 s0, s33, 0xffffff10
	s_cmpk_gt_u32 s0, 0xa7f
	s_cbranch_scc1 .LBB0_770
	v_lshlrev_b32_e32 v2, 2, v1
	v_lshrrev_b32_e32 v3, 3, v188
	v_add_u32_e32 v52, 0, v2
	v_and_b32_e32 v40, 0x78, v3
	v_or_b32_e32 v47, 7, v3
	v_lshl_add_u32 v3, v1, 8, v52
	v_readlane_b32 s12, v254, 0
	v_lshl_add_u32 v48, v40, 2, v3
	v_lshl_add_u32 v49, v47, 2, v3
	v_mov_b32_e32 v3, 0
	v_readlane_b32 s14, v254, 2
	v_readlane_b32 s15, v254, 3
	v_readlane_b32 s16, v254, 4
	v_readlane_b32 s17, v254, 5
	v_lshl_add_u64 v[4:5], s[84:85], 0, v[2:3]
	v_lshl_add_u64 v[8:9], s[72:73], 0, v[2:3]
	v_lshl_add_u64 v[6:7], s[16:17], 0, v[2:3]
	v_lshl_add_u64 v[10:11], s[70:71], 0, v[2:3]
	v_lshl_add_u64 v[12:13], s[68:69], 0, v[2:3]
	v_lshl_add_u64 v[14:15], s[14:15], 0, v[2:3]
	v_lshl_add_u64 v[16:17], s[74:75], 0, v[2:3]
	v_lshlrev_b32_e32 v2, 1, v1
	s_mov_b64 s[2:3], 0xb00000
	v_lshl_add_u64 v[18:19], s[86:87], 0, v[2:3]
	v_lshl_add_u64 v[20:21], v[8:9], 0, s[2:3]
	v_lshl_add_u64 v[24:25], v[10:11], 0, s[2:3]
	v_lshl_add_u64 v[28:29], v[12:13], 0, s[2:3]
	s_mov_b64 s[2:3], 0x1e80000
	v_lshl_add_u64 v[30:31], v[18:19], 0, s[2:3]
	s_mov_b64 s[2:3], 0x1880000
	s_mov_b64 s[6:7], 0x2b80000
	v_lshl_add_u64 v[32:33], v[18:19], 0, s[2:3]
	s_mov_b64 s[2:3], 0x1300000
	s_add_i32 s4, s33, 0xcf0
	v_mul_u32_u24_e32 v51, 0x104, v40
	v_readlane_b32 s13, v254, 1
	v_lshl_add_u64 v[22:23], v[18:19], 0, s[6:7]
	s_mov_b64 s[6:7], 0x2080000
	v_lshl_add_u64 v[34:35], v[18:19], 0, s[2:3]
	s_mov_b64 s[2:3], 0x800000
	v_mul_u32_u24_e32 v53, 0x104, v47
	v_lshl_add_u64 v[26:27], v[18:19], 0, s[6:7]
	v_lshl_add_u64 v[36:37], v[18:19], 0, s[2:3]
	s_mov_b64 s[2:3], 0x600000
	s_lshl_b32 s7, s50, 6
	s_mul_i32 s9, s50, 0x2e000
	v_lshrrev_b32_e32 v2, 6, v188
	s_lshl_b32 s0, s4, 2
	s_lshl_b32 s13, s50, 2
	v_add_u32_e32 v51, v52, v51
	s_mov_b32 s1, 0
	v_or_b32_e32 v41, 1, v40
	v_or_b32_e32 v42, 2, v40
	v_or_b32_e32 v43, 3, v40
	v_or_b32_e32 v44, 4, v40
	v_or_b32_e32 v45, 5, v40
	v_or_b32_e32 v46, 6, v40
	s_add_i32 s5, s50, 0xffffff10
	v_lshl_add_u64 v[38:39], v[18:19], 0, s[2:3]
	s_lshl_b32 s6, s4, 6
	s_addk_i32 s7, 0xc400
	v_mul_u32_u24_e32 v1, 0xb80, v47
	s_mul_i32 s8, s4, 0x2e000
	s_add_i32 s9, s9, 0xfd4e0000
	v_mul_u32_u24_e32 v50, 0x5c00, v2
	s_add_i32 s12, s0, 0x3b480
	s_addk_i32 s13, 0xfc40
	v_add_u32_e32 v52, v52, v53
	s_movk_i32 s14, 0x7fff
	s_mov_b32 s15, 0xfff00
	s_mov_b32 s16, 0x40000
	v_add_u32_e32 v53, 0x400, v51
	v_readlane_b32 s18, v254, 6
	v_readlane_b32 s19, v254, 7
	s_branch .LBB0_734
